# v12: P0 LayerNorm loop double-buffered x loads, LN w/b hoisted, DPP reductions; mem-row loads batched
# speedup vs baseline: 1.0124x; 1.0124x over previous
; DI void ln_row_f32_to_bf16(const float* x, const float* w, const float* bb, bf16_t* o, int lane) {
;     const f32x4* xr = (const f32x4*)x + lane; f32x4 v[4]; float s = 0.f;
; #pragma unroll
;     for (int j = 0; j < 4; ++j) { v[j] = xr[64 * j]; s += (v[j][0] + v[j][1]) + (v[j][2] + v[j][3]); }
;     const float mean = wave_sum(s) * (1.f / 1024.f); float s2 = 0.f;
; #pragma unroll
;     for (int j = 0; j < 4; ++j) { v[j] = v[j] - mean; s2 += (v[j][0] * v[j][0] + v[j][1] * v[j][1]) + (v[j][2] * v[j][2] + v[j][3] * v[j][3]); }
;     const float rstd = __builtin_amdgcn_rsqf(wave_sum(s2) * (1.f / 1024.f) + 1e-5f);
; __global__ void __launch_bounds__(512, 2) fwd_kernel(Params P) {
;     ...
;         for (int m = gw; m < MT; m += NGW) { const float* x = m < MP ? P.in[I_XP] + (size_t)m * 1024 : P.in[I_XS] + (size_t)(m - MP) * 1024; ln_row_f32_to_bf16(x, P.in[I_LN0W], P.in[I_LN0B], XN + (size_t)m * 1024, lane); }
.LBB0_17:
	s_cmp_gt_i32 s44, 0x83ff
	v_mov_b32_e32 v7, 0
	s_cbranch_scc1 .LBB0_22
	v_mbcnt_lo_u32_b32 v1, -1, 0
	v_mbcnt_hi_u32_b32 v2, -1, v1
	v_and_b32_e32 v1, 64, v2
	v_add_u32_e32 v3, 64, v1
	v_xor_b32_e32 v1, 1, v2
	v_cmp_lt_i32_e32 vcc, v1, v3
	v_xor_b32_e32 v4, 2, v2
	v_lshlrev_b32_e32 v6, 4, v182
	v_cndmask_b32_e32 v1, v2, v1, vcc
	v_cmp_lt_i32_e32 vcc, v4, v3
	s_ashr_i32 s45, s44, 31
	s_waitcnt lgkmcnt(0)
	v_lshl_add_u64 v[10:11], s[8:9], 0, v[6:7]
	v_cndmask_b32_e32 v4, v2, v4, vcc
	v_lshlrev_b32_e32 v14, 2, v4
	v_xor_b32_e32 v4, 4, v2
	v_cmp_lt_i32_e32 vcc, v4, v3
	s_ashr_i32 s47, s46, 31
	s_lshl_b64 s[8:9], s[44:45], 12
	v_cndmask_b32_e32 v4, v2, v4, vcc
	v_lshlrev_b32_e32 v15, 2, v4
	v_xor_b32_e32 v4, 8, v2
	v_cmp_lt_i32_e32 vcc, v4, v3
	s_add_u32 s8, s12, s8
	v_lshl_add_u64 v[8:9], s[6:7], 0, v[6:7]
	v_cndmask_b32_e32 v4, v2, v4, vcc
	v_lshlrev_b32_e32 v16, 2, v4
	v_xor_b32_e32 v4, 16, v2
	v_cmp_lt_i32_e32 vcc, v4, v3
	s_mov_b32 s7, 0
	v_lshlrev_b32_e32 v1, 2, v1
	v_cndmask_b32_e32 v4, v2, v4, vcc
	v_lshlrev_b32_e32 v17, 2, v4
	v_xor_b32_e32 v4, 32, v2
	v_cmp_lt_i32_e32 vcc, v4, v3
	v_mov_b32_e32 v3, v7
	s_addc_u32 s9, s13, s9
	v_cndmask_b32_e32 v2, v2, v4, vcc
	v_lshlrev_b32_e32 v18, 2, v2
	v_lshlrev_b32_e32 v2, 3, v182
	v_lshl_add_u64 v[12:13], s[62:63], 0, v[2:3]
	s_lshl_b64 s[10:11], s[46:47], 12
	v_mov_b32_e32 v7, 0x3727c5ac
	s_mov_b64 s[12:13], s[44:45]
	s_lshl_b64 s[34:35], s[44:45], 12
	s_sub_u32 s8, s8, s34
	s_subb_u32 s9, s9, s35
	global_load_dwordx4 v[130:133], v[8:9], off
	global_load_dwordx4 v[134:137], v[8:9], off offset:1024
	global_load_dwordx4 v[138:141], v[8:9], off offset:2048
	global_load_dwordx4 v[142:145], v[8:9], off offset:3072
	global_load_dwordx4 v[146:149], v[10:11], off
	global_load_dwordx4 v[150:153], v[10:11], off offset:1024
	global_load_dwordx4 v[154:157], v[10:11], off offset:2048
	global_load_dwordx4 v[158:161], v[10:11], off offset:3072
	s_mov_b32 s28, s44
	s_add_i32 s29, s44, s46
	s_lshl_b32 s38, s46, 1
	s_min_i32 s6, s28, 0x83ff
	s_add_i32 s34, s6, 0xffff8000
	s_cmp_lt_i32 s6, 0x8000
	s_cselect_b32 s34, s6, s34
	s_cselect_b32 s36, s8, s14
	s_cselect_b32 s37, s9, s15
	s_mov_b32 s35, 0
	s_lshl_b64 s[34:35], s[34:35], 12
	s_add_u32 s36, s36, s34
	s_addc_u32 s37, s37, s35
	global_load_dwordx4 v[20:23], v6, s[36:37]
	global_load_dwordx4 v[24:27], v6, s[36:37] offset:1024
	global_load_dwordx4 v[28:31], v6, s[36:37] offset:2048
	global_load_dwordx4 v[32:35], v6, s[36:37] offset:3072
	s_min_i32 s6, s29, 0x83ff
	s_add_i32 s34, s6, 0xffff8000
	s_cmp_lt_i32 s6, 0x8000
	s_cselect_b32 s34, s6, s34
	s_cselect_b32 s36, s8, s14
	s_cselect_b32 s37, s9, s15
	s_mov_b32 s35, 0
	s_lshl_b64 s[34:35], s[34:35], 12
	s_add_u32 s36, s36, s34
	s_addc_u32 s37, s37, s35
	global_load_dwordx4 v[162:165], v6, s[36:37]
	global_load_dwordx4 v[166:169], v6, s[36:37] offset:1024
	global_load_dwordx4 v[170:173], v6, s[36:37] offset:2048
	global_load_dwordx4 v[174:177], v6, s[36:37] offset:3072
	s_waitcnt vmcnt(4)
.Lp0ln_loop:
	s_waitcnt vmcnt(8)
	s_mov_b32 s34, s28
	s_mov_b32 s35, 0
	s_lshl_b64 s[34:35], s[34:35], 11
	v_lshl_add_u64 v[204:205], v[12:13], 0, s[34:35]
	v_pk_add_f32 v[184:185], v[20:21], v[22:23]
	v_pk_add_f32 v[186:187], v[24:25], v[26:27]
	v_pk_add_f32 v[188:189], v[28:29], v[30:31]
	v_pk_add_f32 v[190:191], v[32:33], v[34:35]
	v_pk_add_f32 v[184:185], v[184:185], v[186:187]
	v_pk_add_f32 v[188:189], v[188:189], v[190:191]
	v_pk_add_f32 v[184:185], v[184:185], v[188:189]
	s_nop 0
	v_add_f32_e32 v192, v184, v185
	s_nop 1
	v_add_f32_dpp v192, v192, v192 quad_perm:[1,0,3,2] row_mask:0xf bank_mask:0xf
	s_nop 1
	v_add_f32_dpp v192, v192, v192 quad_perm:[2,3,0,1] row_mask:0xf bank_mask:0xf
	s_nop 1
	v_add_f32_dpp v192, v192, v192 row_half_mirror row_mask:0xf bank_mask:0xf
	s_nop 1
	v_add_f32_dpp v192, v192, v192 row_mirror row_mask:0xf bank_mask:0xf
	s_nop 1
	v_add_f32_dpp v192, v192, v192 row_bcast:15 row_mask:0xa bank_mask:0xf
	s_nop 1
	v_add_f32_dpp v192, v192, v192 row_bcast:31 row_mask:0xc bank_mask:0xf
	s_nop 1
	v_readlane_b32 s30, v192, 63
	s_nop 1
	v_mov_b32_e32 v194, s30
	v_mul_f32_e32 v194, 0xba800000, v194
	v_pk_add_f32 v[20:21], v[20:21], v[194:195] op_sel_hi:[1,0]
	v_pk_add_f32 v[22:23], v[22:23], v[194:195] op_sel_hi:[1,0]
	v_pk_add_f32 v[24:25], v[24:25], v[194:195] op_sel_hi:[1,0]
	v_pk_add_f32 v[26:27], v[26:27], v[194:195] op_sel_hi:[1,0]
	v_pk_add_f32 v[28:29], v[28:29], v[194:195] op_sel_hi:[1,0]
	v_pk_add_f32 v[30:31], v[30:31], v[194:195] op_sel_hi:[1,0]
	v_pk_add_f32 v[32:33], v[32:33], v[194:195] op_sel_hi:[1,0]
	v_pk_add_f32 v[34:35], v[34:35], v[194:195] op_sel_hi:[1,0]
	v_pk_mul_f32 v[184:185], v[20:21], v[20:21]
	v_pk_mul_f32 v[186:187], v[28:29], v[28:29]
	v_pk_fma_f32 v[184:185], v[22:23], v[22:23], v[184:185]
	v_pk_fma_f32 v[186:187], v[30:31], v[30:31], v[186:187]
	v_pk_fma_f32 v[184:185], v[24:25], v[24:25], v[184:185]
	v_pk_fma_f32 v[186:187], v[32:33], v[32:33], v[186:187]
	v_pk_fma_f32 v[184:185], v[26:27], v[26:27], v[184:185]
	v_pk_fma_f32 v[186:187], v[34:35], v[34:35], v[186:187]
	v_pk_add_f32 v[184:185], v[184:185], v[186:187]
	s_nop 0
	v_add_f32_e32 v192, v184, v185
	s_nop 1
	v_add_f32_dpp v192, v192, v192 quad_perm:[1,0,3,2] row_mask:0xf bank_mask:0xf
	s_nop 1
	v_add_f32_dpp v192, v192, v192 quad_perm:[2,3,0,1] row_mask:0xf bank_mask:0xf
	s_nop 1
	v_add_f32_dpp v192, v192, v192 row_half_mirror row_mask:0xf bank_mask:0xf
	s_nop 1
	v_add_f32_dpp v192, v192, v192 row_mirror row_mask:0xf bank_mask:0xf
	s_nop 1
	v_add_f32_dpp v192, v192, v192 row_bcast:15 row_mask:0xa bank_mask:0xf
	s_nop 1
	v_add_f32_dpp v192, v192, v192 row_bcast:31 row_mask:0xc bank_mask:0xf
	s_nop 1
; DI unsigned pk2(float lo, float hi) { f32x2 v = {lo, hi}; bfv2 b = __builtin_convertvector(v, bfv2); return __builtin_bit_cast(unsigned, b); }
; DI void ln_row_f32_to_bf16(const float* x, const float* w, const float* bb, bf16_t* o, int lane) {
;     ...
;     const float rstd = __builtin_amdgcn_rsqf(wave_sum(s2) * (1.f / 1024.f) + 1e-5f);
; #pragma unroll
;     for (int j = 0; j < 4; ++j) { const f32x4 ww = ((const f32x4*)w)[64 * j + lane], bv = ((const f32x4*)bb)[64 * j + lane]; const f32x4 y = v[j] * rstd * ww + bv;
;         u32x2 p; p.x = pk2(y[0], y[1]); p.y = pk2(y[2], y[3]); ((u32x2*)o)[64 * j + lane] = p; }
; __global__ void __launch_bounds__(512, 2) fwd_kernel(Params P) {
;     ...
;         for (int m = gw; m < MT; m += NGW) { const float* x = m < MP ? P.in[I_XP] + (size_t)m * 1024 : P.in[I_XS] + (size_t)(m - MP) * 1024; ln_row_f32_to_bf16(x, P.in[I_LN0W], P.in[I_LN0B], XN + (size_t)m * 1024, lane); }
	v_readlane_b32 s30, v192, 63
	s_nop 1
	v_mov_b32_e32 v194, s30
	v_fmamk_f32 v194, v194, 0x3a800000, v7
	v_rsq_f32_e32 v194, v194
	s_nop 0
	v_pk_mul_f32 v[20:21], v[20:21], v[194:195] op_sel_hi:[1,0]
	v_pk_mul_f32 v[22:23], v[22:23], v[194:195] op_sel_hi:[1,0]
	v_pk_mul_f32 v[24:25], v[24:25], v[194:195] op_sel_hi:[1,0]
	v_pk_mul_f32 v[26:27], v[26:27], v[194:195] op_sel_hi:[1,0]
	v_pk_mul_f32 v[28:29], v[28:29], v[194:195] op_sel_hi:[1,0]
	v_pk_mul_f32 v[30:31], v[30:31], v[194:195] op_sel_hi:[1,0]
	v_pk_mul_f32 v[32:33], v[32:33], v[194:195] op_sel_hi:[1,0]
	v_pk_mul_f32 v[34:35], v[34:35], v[194:195] op_sel_hi:[1,0]
	v_pk_fma_f32 v[184:185], v[130:131], v[20:21], v[146:147]
	v_pk_fma_f32 v[186:187], v[132:133], v[22:23], v[148:149]
	v_cvt_pk_bf16_f32 v196, v184, v185
	v_cvt_pk_bf16_f32 v197, v186, v187
	global_store_dwordx2 v[204:205], v[196:197], off
	v_pk_fma_f32 v[188:189], v[134:135], v[24:25], v[150:151]
	v_pk_fma_f32 v[190:191], v[136:137], v[26:27], v[152:153]
	v_cvt_pk_bf16_f32 v198, v188, v189
	v_cvt_pk_bf16_f32 v199, v190, v191
	global_store_dwordx2 v[204:205], v[198:199], off offset:512
	v_pk_fma_f32 v[184:185], v[138:139], v[28:29], v[154:155]
	v_pk_fma_f32 v[186:187], v[140:141], v[30:31], v[156:157]
	v_cvt_pk_bf16_f32 v200, v184, v185
	v_cvt_pk_bf16_f32 v201, v186, v187
	global_store_dwordx2 v[204:205], v[200:201], off offset:1024
	v_pk_fma_f32 v[188:189], v[142:143], v[32:33], v[158:159]
	v_pk_fma_f32 v[190:191], v[144:145], v[34:35], v[160:161]
	v_cvt_pk_bf16_f32 v202, v188, v189
	v_cvt_pk_bf16_f32 v203, v190, v191
	global_store_dwordx2 v[204:205], v[202:203], off offset:1536
	s_add_i32 s28, s28, s38
	s_min_i32 s6, s28, 0x83ff
	s_add_i32 s34, s6, 0xffff8000
	s_cmp_lt_i32 s6, 0x8000
	s_cselect_b32 s34, s6, s34
	s_cselect_b32 s36, s8, s14
	s_cselect_b32 s37, s9, s15
	s_mov_b32 s35, 0
	s_lshl_b64 s[34:35], s[34:35], 12
	s_add_u32 s36, s36, s34
	s_addc_u32 s37, s37, s35
	global_load_dwordx4 v[20:23], v6, s[36:37]
	global_load_dwordx4 v[24:27], v6, s[36:37] offset:1024
	global_load_dwordx4 v[28:31], v6, s[36:37] offset:2048
	global_load_dwordx4 v[32:35], v6, s[36:37] offset:3072
	s_cmp_gt_i32 s29, 0x83ff
	s_cbranch_scc1 .Lp0ln_done
; DI unsigned pk2(float lo, float hi) { f32x2 v = {lo, hi}; bfv2 b = __builtin_convertvector(v, bfv2); return __builtin_bit_cast(unsigned, b); }
; DI void ln_row_f32_to_bf16(const float* x, const float* w, const float* bb, bf16_t* o, int lane) {
;     const f32x4* xr = (const f32x4*)x + lane; f32x4 v[4]; float s = 0.f;
; #pragma unroll
;     for (int j = 0; j < 4; ++j) { v[j] = xr[64 * j]; s += (v[j][0] + v[j][1]) + (v[j][2] + v[j][3]); }
;     const float mean = wave_sum(s) * (1.f / 1024.f); float s2 = 0.f;
; #pragma unroll
;     for (int j = 0; j < 4; ++j) { v[j] = v[j] - mean; s2 += (v[j][0] * v[j][0] + v[j][1] * v[j][1]) + (v[j][2] * v[j][2] + v[j][3] * v[j][3]); }
;     const float rstd = __builtin_amdgcn_rsqf(wave_sum(s2) * (1.f / 1024.f) + 1e-5f);
; #pragma unroll
;     for (int j = 0; j < 4; ++j) { const f32x4 ww = ((const f32x4*)w)[64 * j + lane], bv = ((const f32x4*)bb)[64 * j + lane]; const f32x4 y = v[j] * rstd * ww + bv;
;         u32x2 p; p.x = pk2(y[0], y[1]); p.y = pk2(y[2], y[3]); ((u32x2*)o)[64 * j + lane] = p; }
; __global__ void __launch_bounds__(512, 2) fwd_kernel(Params P) {
;     ...
;         for (int m = gw; m < MT; m += NGW) { const float* x = m < MP ? P.in[I_XP] + (size_t)m * 1024 : P.in[I_XS] + (size_t)(m - MP) * 1024; ln_row_f32_to_bf16(x, P.in[I_LN0W], P.in[I_LN0B], XN + (size_t)m * 1024, lane); }
;         for (int m = gw; m < 2048; m += NGW) { const f32x4* xr = (const f32x4*)(P.in[I_MEM] + (size_t)m * 1024) + lane; u32x2* o = (u32x2*)(XN + (size_t)(MT + m) * 1024) + lane;
; #pragma unroll
;             for (int j = 0; j < 4; ++j) { const f32x4 v = xr[64 * j]; u32x2 p; p.x = pk2(v[0], v[1]); p.y = pk2(v[2], v[3]); o[64 * j] = p; } }
	s_waitcnt vmcnt(8)
	s_mov_b32 s34, s29
	s_mov_b32 s35, 0
	s_lshl_b64 s[34:35], s[34:35], 11
	v_lshl_add_u64 v[204:205], v[12:13], 0, s[34:35]
	v_pk_add_f32 v[184:185], v[162:163], v[164:165]
	v_pk_add_f32 v[186:187], v[166:167], v[168:169]
	v_pk_add_f32 v[188:189], v[170:171], v[172:173]
	v_pk_add_f32 v[190:191], v[174:175], v[176:177]
	v_pk_add_f32 v[184:185], v[184:185], v[186:187]
	v_pk_add_f32 v[188:189], v[188:189], v[190:191]
	v_pk_add_f32 v[184:185], v[184:185], v[188:189]
	s_nop 0
	v_add_f32_e32 v192, v184, v185
	s_nop 1
	v_add_f32_dpp v192, v192, v192 quad_perm:[1,0,3,2] row_mask:0xf bank_mask:0xf
	s_nop 1
	v_add_f32_dpp v192, v192, v192 quad_perm:[2,3,0,1] row_mask:0xf bank_mask:0xf
	s_nop 1
	v_add_f32_dpp v192, v192, v192 row_half_mirror row_mask:0xf bank_mask:0xf
	s_nop 1
	v_add_f32_dpp v192, v192, v192 row_mirror row_mask:0xf bank_mask:0xf
	s_nop 1
	v_add_f32_dpp v192, v192, v192 row_bcast:15 row_mask:0xa bank_mask:0xf
	s_nop 1
	v_add_f32_dpp v192, v192, v192 row_bcast:31 row_mask:0xc bank_mask:0xf
	s_nop 1
	v_readlane_b32 s30, v192, 63
	s_nop 1
	v_mov_b32_e32 v194, s30
	v_mul_f32_e32 v194, 0xba800000, v194
	v_pk_add_f32 v[162:163], v[162:163], v[194:195] op_sel_hi:[1,0]
	v_pk_add_f32 v[164:165], v[164:165], v[194:195] op_sel_hi:[1,0]
	v_pk_add_f32 v[166:167], v[166:167], v[194:195] op_sel_hi:[1,0]
	v_pk_add_f32 v[168:169], v[168:169], v[194:195] op_sel_hi:[1,0]
	v_pk_add_f32 v[170:171], v[170:171], v[194:195] op_sel_hi:[1,0]
	v_pk_add_f32 v[172:173], v[172:173], v[194:195] op_sel_hi:[1,0]
	v_pk_add_f32 v[174:175], v[174:175], v[194:195] op_sel_hi:[1,0]
	v_pk_add_f32 v[176:177], v[176:177], v[194:195] op_sel_hi:[1,0]
	v_pk_mul_f32 v[184:185], v[162:163], v[162:163]
	v_pk_mul_f32 v[186:187], v[170:171], v[170:171]
	v_pk_fma_f32 v[184:185], v[164:165], v[164:165], v[184:185]
	v_pk_fma_f32 v[186:187], v[172:173], v[172:173], v[186:187]
	v_pk_fma_f32 v[184:185], v[166:167], v[166:167], v[184:185]
	v_pk_fma_f32 v[186:187], v[174:175], v[174:175], v[186:187]
	v_pk_fma_f32 v[184:185], v[168:169], v[168:169], v[184:185]
	v_pk_fma_f32 v[186:187], v[176:177], v[176:177], v[186:187]
	v_pk_add_f32 v[184:185], v[184:185], v[186:187]
	s_nop 0
	v_add_f32_e32 v192, v184, v185
	s_nop 1
	v_add_f32_dpp v192, v192, v192 quad_perm:[1,0,3,2] row_mask:0xf bank_mask:0xf
	s_nop 1
	v_add_f32_dpp v192, v192, v192 quad_perm:[2,3,0,1] row_mask:0xf bank_mask:0xf
	s_nop 1
	v_add_f32_dpp v192, v192, v192 row_half_mirror row_mask:0xf bank_mask:0xf
	s_nop 1
	v_add_f32_dpp v192, v192, v192 row_mirror row_mask:0xf bank_mask:0xf
	s_nop 1
	v_add_f32_dpp v192, v192, v192 row_bcast:15 row_mask:0xa bank_mask:0xf
	s_nop 1
	v_add_f32_dpp v192, v192, v192 row_bcast:31 row_mask:0xc bank_mask:0xf
	s_nop 1
	v_readlane_b32 s30, v192, 63
	s_nop 1
	v_mov_b32_e32 v194, s30
	v_fmamk_f32 v194, v194, 0x3a800000, v7
	v_rsq_f32_e32 v194, v194
	s_nop 0
	v_pk_mul_f32 v[162:163], v[162:163], v[194:195] op_sel_hi:[1,0]
	v_pk_mul_f32 v[164:165], v[164:165], v[194:195] op_sel_hi:[1,0]
	v_pk_mul_f32 v[166:167], v[166:167], v[194:195] op_sel_hi:[1,0]
	v_pk_mul_f32 v[168:169], v[168:169], v[194:195] op_sel_hi:[1,0]
	v_pk_mul_f32 v[170:171], v[170:171], v[194:195] op_sel_hi:[1,0]
	v_pk_mul_f32 v[172:173], v[172:173], v[194:195] op_sel_hi:[1,0]
	v_pk_mul_f32 v[174:175], v[174:175], v[194:195] op_sel_hi:[1,0]
	v_pk_mul_f32 v[176:177], v[176:177], v[194:195] op_sel_hi:[1,0]
	v_pk_fma_f32 v[184:185], v[130:131], v[162:163], v[146:147]
	v_pk_fma_f32 v[186:187], v[132:133], v[164:165], v[148:149]
	v_cvt_pk_bf16_f32 v196, v184, v185
	v_cvt_pk_bf16_f32 v197, v186, v187
	global_store_dwordx2 v[204:205], v[196:197], off
	v_pk_fma_f32 v[188:189], v[134:135], v[166:167], v[150:151]
	v_pk_fma_f32 v[190:191], v[136:137], v[168:169], v[152:153]
	v_cvt_pk_bf16_f32 v198, v188, v189
	v_cvt_pk_bf16_f32 v199, v190, v191
	global_store_dwordx2 v[204:205], v[198:199], off offset:512
	v_pk_fma_f32 v[184:185], v[138:139], v[170:171], v[154:155]
	v_pk_fma_f32 v[186:187], v[140:141], v[172:173], v[156:157]
	v_cvt_pk_bf16_f32 v200, v184, v185
	v_cvt_pk_bf16_f32 v201, v186, v187
	global_store_dwordx2 v[204:205], v[200:201], off offset:1024
	v_pk_fma_f32 v[188:189], v[142:143], v[174:175], v[158:159]
	v_pk_fma_f32 v[190:191], v[144:145], v[176:177], v[160:161]
	v_cvt_pk_bf16_f32 v202, v188, v189
	v_cvt_pk_bf16_f32 v203, v190, v191
	global_store_dwordx2 v[204:205], v[202:203], off offset:1536
	s_add_i32 s29, s29, s38
	s_min_i32 s6, s29, 0x83ff
	s_add_i32 s34, s6, 0xffff8000
	s_cmp_lt_i32 s6, 0x8000
	s_cselect_b32 s34, s6, s34
	s_cselect_b32 s36, s8, s14
	s_cselect_b32 s37, s9, s15
	s_mov_b32 s35, 0
	s_lshl_b64 s[34:35], s[34:35], 12
	s_add_u32 s36, s36, s34
	s_addc_u32 s37, s37, s35
	global_load_dwordx4 v[162:165], v6, s[36:37]
	global_load_dwordx4 v[166:169], v6, s[36:37] offset:1024
	global_load_dwordx4 v[170:173], v6, s[36:37] offset:2048
	global_load_dwordx4 v[174:177], v6, s[36:37] offset:3072
	s_cmp_le_i32 s28, 0x83ff
	s_cbranch_scc1 .Lp0ln_loop
.Lp0ln_done:
	s_waitcnt vmcnt(0)
.LBB0_22:
	s_cmpk_gt_i32 s44, 0x7ff
	s_cbranch_scc1 .LBB0_25
	s_waitcnt lgkmcnt(0)
	s_add_i32 s6, s44, 0x8400
	s_ashr_i32 s7, s6, 31
	s_lshl_b64 s[6:7], s[6:7], 11
	s_add_u32 s6, s42, s6
	v_lshlrev_b32_e32 v4, 3, v182
	v_mov_b32_e32 v5, 0
	s_addc_u32 s7, s43, s7
	v_lshl_add_u64 v[2:3], s[6:7], 0, v[4:5]
	s_mov_b64 s[6:7], 0x2400600
	s_ashr_i32 s47, s46, 31
	s_ashr_i32 s45, s44, 31
	v_lshl_add_u64 v[2:3], v[2:3], 0, s[6:7]
	s_lshl_b64 s[6:7], s[46:47], 11
	s_lshl_b64 s[8:9], s[44:45], 12
	s_add_u32 s4, s4, s8
	v_lshlrev_b32_e32 v4, 4, v182
	s_addc_u32 s5, s5, s9
	v_lshl_add_u64 v[4:5], s[4:5], 0, v[4:5]
	s_mov_b64 s[4:5], 0x800
	v_lshl_add_u64 v[4:5], v[4:5], 0, s[4:5]
	s_lshl_b64 s[4:5], s[46:47], 12
	s_mov_b32 s3, s44
.LBB0_24:
	global_load_dwordx4 v[184:187], v[4:5], off offset:-2048
	global_load_dwordx4 v[188:191], v[4:5], off offset:-1024
	global_load_dwordx4 v[192:195], v[4:5], off
	global_load_dwordx4 v[196:199], v[4:5], off offset:1024
	s_add_i32 s3, s3, s46
	s_cmpk_gt_i32 s3, 0x7ff
	v_lshl_add_u64 v[4:5], v[4:5], 0, s[4:5]
	s_waitcnt vmcnt(3)
	v_cvt_pk_bf16_f32 v200, v184, v185
	v_cvt_pk_bf16_f32 v201, v186, v187
	global_store_dwordx2 v[2:3], v[200:201], off offset:-1536
	s_waitcnt vmcnt(3)
	v_cvt_pk_bf16_f32 v202, v188, v189
	v_cvt_pk_bf16_f32 v203, v190, v191
	global_store_dwordx2 v[2:3], v[202:203], off offset:-1024
	s_waitcnt vmcnt(3)
	v_cvt_pk_bf16_f32 v204, v192, v193
	v_cvt_pk_bf16_f32 v205, v194, v195
	global_store_dwordx2 v[2:3], v[204:205], off offset:-512
	s_waitcnt vmcnt(3)
	v_cvt_pk_bf16_f32 v206, v196, v197
	v_cvt_pk_bf16_f32 v207, v198, v199
	global_store_dwordx2 v[2:3], v[206:207], off
	v_lshl_add_u64 v[2:3], v[2:3], 0, s[6:7]
	s_cbranch_scc0 .LBB0_24
